# speedup vs baseline: 1.0145x; 1.0097x over previous
; #define WAIT_V(n) asm volatile("s_waitcnt vmcnt(%0)" ::"n"(n) : "memory")
; #define STAGE(P, BASE, OFF, kt) do { \
;     __builtin_amdgcn_global_load_lds((const unsigned*)((BASE) + (OFF[0] + (unsigned)(kt) * BK)), (unsigned*)((char*)(P) + wid * 1024), 16, 0, 0); \
;     __builtin_amdgcn_global_load_lds((const unsigned*)((BASE) + (OFF[1] + (unsigned)(kt) * BK)), (unsigned*)((char*)(P) + wid * 1024 + 8192), 16, 0, 0); } while (0)
; #define BAR __builtin_amdgcn_s_barrier()
; DEVI void gemm_tile(const Params& p, int layer, const u16* __restrict__ A, unsigned lda, const u16* __restrict__ Bt, unsigned ldb, int K,
;                     int brow, int bcol, int ekind, const int tid_) {
;     ...
;   const int wid = tid_ >> 6, lane = tid_ & 63, wr = wid >> 2, wc = wid & 3, fr = lane & 15, fq = lane >> 4;
;   unsigned offA[2], offB[2];
; #pragma unroll
;   for (int i = 0; i < 2; ++i) { int R, C; stage_rc8(tid_ * 16 + i * 8192, R, C); offA[i] = (unsigned)R * lda + C; offB[i] = (unsigned)R * ldb + C; }
;   const u16* A0 = A + (size_t)brow * lda; const u16* A1 = A + (size_t)(brow + HALF) * lda;
;   const u16* B0p = Bt + (size_t)bcol * ldb; const u16* B1p = Bt + (size_t)(bcol + HALF) * ldb;
;   f32x4 acc[2][2][4][2] = {};
;   bf16x8 At[4][2], B0[2][2], B1[2][2];
;   const int nt = K / BK;
;   STAGE(SB(0, 0), B0p, offB, 0); STAGE(SA(0, 0), A0, offA, 0);
;   STAGE(SB(0, 1), B1p, offB, 0); STAGE(SA(0, 1), A1, offA, 0);
;   if (wr == 1) BAR;
;   WAIT_V(4); BAR;
;   STAGE(SB(1, 0), B0p, offB, 1); STAGE(SA(1, 0), A0, offA, 1); STAGE(SB(1, 1), B1p, offB, 1);
;   WAIT_V(6); BAR;
;   for (int t = 0; t < nt - 2; t += 2) {
.LBB0_312:
	s_or_b64 exec, exec, s[10:11]
	v_readlane_b32 s42, v254, 45
	v_add_u32_e32 v0, 64, v0
	v_lshlrev_b64 v[12:13], 1, v[0:1]
	v_add_u32_e32 v153, s42, v10
	v_lshl_add_u64 v[14:15], s[6:7], 0, v[12:13]
	v_readfirstlane_b32 s11, v153
	s_mov_b32 m0, s11
	v_add_u32_e32 v0, 64, v134
	v_add_u32_e32 v154, 0x2000, v153
	s_waitcnt vmcnt(4)
	s_barrier
	global_load_lds_dwordx4 v[14:15], off
	v_lshlrev_b64 v[14:15], 1, v[0:1]
	v_readfirstlane_b32 s11, v154
	v_add_u32_e32 v155, 0x8000, v145
	v_lshl_add_u64 v[16:17], s[6:7], 0, v[14:15]
	s_mov_b32 m0, s11
	v_add_u32_e32 v0, 64, v130
	v_readfirstlane_b32 s11, v155
	v_add_u32_e32 v157, 0xa000, v145
	v_readlane_b32 s45, v254, 46
	global_load_lds_dwordx4 v[16:17], off
	v_lshl_add_u64 v[16:17], v[0:1], 1, s[4:5]
	s_mov_b32 m0, s11
	v_add_u32_e32 v0, 64, v132
	v_readfirstlane_b32 s11, v157
	v_add_u32_e32 v158, s45, v10
	global_load_lds_dwordx4 v[16:17], off
	v_lshl_add_u64 v[16:17], v[0:1], 1, s[4:5]
	s_mov_b32 m0, s11
	v_readfirstlane_b32 s11, v158
	v_add_u32_e32 v159, 0x2000, v158
	global_load_lds_dwordx4 v[16:17], off
	v_lshl_add_u64 v[12:13], s[8:9], 0, v[12:13]
	s_mov_b32 m0, s11
	v_readfirstlane_b32 s11, v159
	global_load_lds_dwordx4 v[12:13], off
	v_lshl_add_u64 v[12:13], s[8:9], 0, v[14:15]
	s_mov_b32 m0, s11
	v_and_b32_e32 v135, 15, v136
	global_load_lds_dwordx4 v[12:13], off
	v_bfe_u32 v133, v136, 4, 2
	v_lshlrev_b32_e32 v12, 2, v136
	v_and_b32_e32 v131, 3, v9
	v_lshlrev_b32_e32 v9, 4, v133
	v_lshlrev_b32_e32 v10, 6, v135
	v_and_b32_e32 v12, 32, v12
	v_lshlrev_b32_e32 v17, 6, v136
	s_movk_i32 s11, 0x3c0
	s_waitcnt vmcnt(6)
	v_bitop3_b32 v10, v9, v12, v10 bitop3:0x36
	v_lshlrev_b32_e32 v137, 6, v11
	v_lshlrev_b32_e32 v11, 13, v11
	v_and_or_b32 v9, v17, s11, v9
	s_lshr_b32 s10, s66, 6
	v_lshlrev_b32_e32 v0, 12, v131
	v_add_u32_e32 v13, s31, v10
	v_add_u32_e32 v14, s50, v10
	v_add_u32_e32 v15, s42, v10
	v_add_u32_e32 v16, s45, v10
	v_add_u32_e32 v10, 0, v10
	v_xad_u32 v9, v9, v12, 0
	v_or_b32_e32 v12, 0x800, v11
	v_or_b32_e32 v17, 0x1000, v11
	v_or_b32_e32 v18, 0x1800, v11
	v_add3_u32 v162, v4, v2, v3
	v_add3_u32 v163, v5, v2, v3
	v_mov_b32_e32 v2, 0
	s_add_i32 s10, s10, -2
	v_add3_u32 v160, v8, v6, v7
	s_mov_b32 s11, 0
	v_add_u32_e32 v161, v13, v0
	v_add_u32_e32 v141, v10, v11
	v_add_u32_e32 v140, v9, v12
	v_add_u32_e32 v139, v9, v17
	v_add_u32_e32 v138, v9, v18
	v_add_u32_e32 v156, v14, v0
	v_add_u32_e32 v147, v15, v0
	v_add_u32_e32 v142, v16, v0
	s_mov_b32 s42, 0
	v_mov_b32_e32 v3, v2
	v_mov_b32_e32 v4, v2
	v_mov_b32_e32 v5, v2
	v_mov_b32_e32 v6, v2
	v_mov_b32_e32 v7, v2
	v_mov_b32_e32 v8, v2
	v_mov_b32_e32 v9, v2
	v_mov_b32_e32 v10, v2
	v_mov_b32_e32 v11, v2
	v_mov_b32_e32 v12, v2
	v_mov_b32_e32 v13, v2
	v_mov_b32_e32 v14, v2
	v_mov_b32_e32 v15, v2
	v_mov_b32_e32 v16, v2
	v_mov_b32_e32 v17, v2
	v_mov_b32_e32 v18, v2
	v_mov_b32_e32 v19, v2
	v_mov_b32_e32 v20, v2
	v_mov_b32_e32 v21, v2
	v_mov_b32_e32 v22, v2
	v_mov_b32_e32 v23, v2
	v_mov_b32_e32 v24, v2
	v_mov_b32_e32 v25, v2
	v_mov_b32_e32 v26, v2
	v_mov_b32_e32 v27, v2
	v_mov_b32_e32 v28, v2
	v_mov_b32_e32 v29, v2
	v_mov_b32_e32 v30, v2
	v_mov_b32_e32 v31, v2
	v_mov_b32_e32 v32, v2
	v_mov_b32_e32 v33, v2
	v_mov_b32_e32 v34, v2
	v_mov_b32_e32 v35, v2
	v_mov_b32_e32 v36, v2
	v_mov_b32_e32 v37, v2
	v_mov_b32_e32 v38, v2
	v_mov_b32_e32 v39, v2
	v_mov_b32_e32 v40, v2
	v_mov_b32_e32 v41, v2
	v_mov_b32_e32 v42, v2
	v_mov_b32_e32 v43, v2
	v_mov_b32_e32 v44, v2
	v_mov_b32_e32 v45, v2
	v_mov_b32_e32 v46, v2
	v_mov_b32_e32 v47, v2
	v_mov_b32_e32 v48, v2
	v_mov_b32_e32 v49, v2
	v_mov_b32_e32 v50, v2
	v_mov_b32_e32 v51, v2
	v_mov_b32_e32 v52, v2
	v_mov_b32_e32 v53, v2
	v_mov_b32_e32 v54, v2
	v_mov_b32_e32 v55, v2
	v_mov_b32_e32 v56, v2
	v_mov_b32_e32 v57, v2
	v_mov_b32_e32 v58, v2
	v_mov_b32_e32 v59, v2
	v_mov_b32_e32 v60, v2
	v_mov_b32_e32 v61, v2
	v_mov_b32_e32 v62, v2
	v_mov_b32_e32 v63, v2
	v_mov_b32_e32 v64, v2
	v_mov_b32_e32 v65, v2
	v_mov_b32_e32 v66, v2
	v_mov_b32_e32 v67, v2
	v_mov_b32_e32 v68, v2
	v_mov_b32_e32 v69, v2
	v_mov_b32_e32 v70, v2
	v_mov_b32_e32 v71, v2
	v_mov_b32_e32 v72, v2
	v_mov_b32_e32 v73, v2
	v_mov_b32_e32 v74, v2
	v_mov_b32_e32 v75, v2
	v_mov_b32_e32 v76, v2
	v_mov_b32_e32 v77, v2
	v_mov_b32_e32 v78, v2
	v_mov_b32_e32 v79, v2
	v_mov_b32_e32 v80, v2
	v_mov_b32_e32 v81, v2
	v_mov_b32_e32 v82, v2
	v_mov_b32_e32 v83, v2
	v_mov_b32_e32 v84, v2
	v_mov_b32_e32 v85, v2
	v_mov_b32_e32 v86, v2
	v_mov_b32_e32 v87, v2
	v_mov_b32_e32 v88, v2
	v_mov_b32_e32 v89, v2
	v_mov_b32_e32 v90, v2
	v_mov_b32_e32 v91, v2
	v_mov_b32_e32 v92, v2
	v_mov_b32_e32 v93, v2
	v_mov_b32_e32 v94, v2
	v_mov_b32_e32 v95, v2
	v_mov_b32_e32 v96, v2
	v_mov_b32_e32 v97, v2
	v_mov_b32_e32 v98, v2
	v_mov_b32_e32 v99, v2
	v_mov_b32_e32 v100, v2
	v_mov_b32_e32 v101, v2
	v_mov_b32_e32 v102, v2
	v_mov_b32_e32 v103, v2
	v_mov_b32_e32 v104, v2
	v_mov_b32_e32 v105, v2
	v_mov_b32_e32 v106, v2
	v_mov_b32_e32 v107, v2
	v_mov_b32_e32 v108, v2
	v_mov_b32_e32 v109, v2
	v_mov_b32_e32 v110, v2
	v_mov_b32_e32 v111, v2
	v_mov_b32_e32 v112, v2
	v_mov_b32_e32 v113, v2
	v_mov_b32_e32 v114, v2
	v_mov_b32_e32 v115, v2
	v_mov_b32_e32 v116, v2
	v_mov_b32_e32 v117, v2
	v_mov_b32_e32 v118, v2
	v_mov_b32_e32 v119, v2
	v_mov_b32_e32 v120, v2
	v_mov_b32_e32 v121, v2
	v_mov_b32_e32 v122, v2
	v_mov_b32_e32 v123, v2
	v_mov_b32_e32 v124, v2
	v_mov_b32_e32 v125, v2
	v_mov_b32_e32 v126, v2
	v_mov_b32_e32 v127, v2
	v_mov_b32_e32 v128, v2
	v_mov_b32_e32 v129, v2
	s_barrier
	v_readfirstlane_b32 s45, v145
	v_add_u32_e32 v164, 0xc000, v145
	v_add_u32_e32 v165, 0xe000, v145
	v_lshlrev_b32_e32 v166, 1, v162
	v_add_u32_e32 v166, 0x80, v166
	v_lshlrev_b32_e32 v167, 1, v160
	v_add_u32_e32 v167, 0x80, v167
	v_lshlrev_b32_e32 v168, 1, v162
	v_add_u32_e32 v168, 0x100, v168
	v_lshlrev_b32_e32 v169, 1, v160
	v_add_u32_e32 v169, 0x100, v169
	v_lshlrev_b32_e32 v179, 1, v162
	v_add_u32_e32 v179, 0x180, v179
	v_lshlrev_b32_e32 v244, 1, v160
	v_add_u32_e32 v244, 0x180, v244
	v_lshlrev_b32_e32 v245, 1, v163
	v_add_u32_e32 v245, 0x100, v245
	v_lshlrev_b32_e32 v246, 1, v134
	v_add_u32_e32 v246, 0x100, v246
	v_lshlrev_b32_e32 v247, 1, v163
	v_add_u32_e32 v247, 0x180, v247
	v_lshlrev_b32_e32 v248, 1, v134
	v_add_u32_e32 v248, 0x180, v248
; #define WAIT_V(n) asm volatile("s_waitcnt vmcnt(%0)" ::"n"(n) : "memory")
; #define WAIT_L(n) asm volatile("s_waitcnt lgkmcnt(%0)" ::"n"(n) : "memory")
; #define STAGE(P, BASE, OFF, kt) do { \
;     __builtin_amdgcn_global_load_lds((const unsigned*)((BASE) + (OFF[0] + (unsigned)(kt) * BK)), (unsigned*)((char*)(P) + wid * 1024), 16, 0, 0); \
;     __builtin_amdgcn_global_load_lds((const unsigned*)((BASE) + (OFF[1] + (unsigned)(kt) * BK)), (unsigned*)((char*)(P) + wid * 1024 + 8192), 16, 0, 0); } while (0)
; #define LDA(dst, b, h) for (int m = 0; m < 4; ++m) for (int k = 0; k < 2; ++k) \
;     dst[m][k] = *reinterpret_cast<const bf16x8*>((char*)SA(b, h) + lds_byte(wr * 64 + m * 16 + fr, k * 32 + fq * 8))
; #define LDB(dst, b, h) for (int n = 0; n < 2; ++n) for (int k = 0; k < 2; ++k) \
;     dst[n][k] = *reinterpret_cast<const bf16x8*>((char*)SB(b, h) + lds_byte(wc * 32 + n * 16 + fr, k * 32 + fq * 8))
; #define MMA(ai, bj, At_, Bt_) do { __builtin_amdgcn_s_setprio(1); \
;     for (int m = 0; m < 4; ++m) for (int n = 0; n < 2; ++n) for (int k = 0; k < 2; ++k) \
;       acc[ai][bj][m][n] = __builtin_amdgcn_mfma_f32_16x16x32_bf16(Bt_[n][k], At_[m][k], acc[ai][bj][m][n], 0, 0, 0); \
;     __builtin_amdgcn_s_setprio(0); } while (0)
; #define BAR __builtin_amdgcn_s_barrier()
; #define SCHED __builtin_amdgcn_sched_barrier(0)
; DEVI void gemm_tile(const Params& p, int layer, const u16* __restrict__ A, unsigned lda, const u16* __restrict__ Bt, unsigned ldb, int K,
;                     int brow, int bcol, int ekind, const int tid_) {
;     ...
;   for (int t = 0; t < nt - 2; t += 2) {
;     LDB(B0, 0, 0); SCHED; LDA(At, 0, 0); STAGE(SA(1, 1), A1, offA, t + 1);
;     WAIT_L(8); BAR; WAIT_L(0); MMA(0, 0, At, B0); BAR; SCHED;
;     LDB(B1, 0, 1); STAGE(SB(0, 0), B0p, offB, t + 2);
;     BAR; WAIT_L(0); MMA(0, 1, At, B1); BAR;
;     LDA(At, 0, 1); STAGE(SA(0, 0), A0, offA, t + 2);
;     BAR; WAIT_L(0); MMA(1, 0, At, B0); BAR; SCHED;
;     STAGE(SB(0, 1), B1p, offB, t + 2);
;     WAIT_V(6); BAR; MMA(1, 1, At, B1); BAR;
.LBB0_313:
	s_lshl_b32 s50, s11, 1
	ds_read_b128 v[180:183], v161
	ds_read_b128 v[184:187], v161 offset:1024
	ds_read_b128 v[188:191], v161 offset:2048
	ds_read_b128 v[192:195], v161 offset:3072
	s_add_i32 m0, s45, 0xc000
	s_add_u32 s30, s2, s50
	s_addc_u32 s31, s3, 0
	ds_read_b128 v[196:199], v141
	ds_read_b128 v[200:203], v141 offset:1024
	ds_read_b128 v[204:207], v140
	ds_read_b128 v[208:211], v140 offset:1024
	ds_read_b128 v[212:215], v139
	ds_read_b128 v[216:219], v139 offset:1024
	ds_read_b128 v[220:223], v138
	ds_read_b128 v[224:227], v138 offset:1024
	global_load_lds_dwordx4 v166, s[30:31]
	s_add_i32 m0, s45, 0xe000
	s_nop 0
	global_load_lds_dwordx4 v167, s[30:31]
	s_waitcnt lgkmcnt(8)
	s_barrier
	s_waitcnt lgkmcnt(0)
	s_setprio 1
	v_mfma_f32_16x16x32_bf16 v[126:129], v[180:183], v[196:199], v[126:129]
	v_mfma_f32_16x16x32_bf16 v[122:125], v[188:191], v[196:199], v[122:125]
	v_mfma_f32_16x16x32_bf16 v[118:121], v[180:183], v[204:207], v[118:121]
	v_mfma_f32_16x16x32_bf16 v[114:117], v[188:191], v[204:207], v[114:117]
	v_mfma_f32_16x16x32_bf16 v[110:113], v[180:183], v[212:215], v[110:113]
	v_mfma_f32_16x16x32_bf16 v[106:109], v[188:191], v[212:215], v[106:109]
	v_mfma_f32_16x16x32_bf16 v[102:105], v[180:183], v[220:223], v[102:105]
	v_mfma_f32_16x16x32_bf16 v[98:101], v[188:191], v[220:223], v[98:101]
	v_mfma_f32_16x16x32_bf16 v[126:129], v[184:187], v[200:203], v[126:129]
	v_mfma_f32_16x16x32_bf16 v[122:125], v[192:195], v[200:203], v[122:125]
	v_mfma_f32_16x16x32_bf16 v[118:121], v[184:187], v[208:211], v[118:121]
	v_mfma_f32_16x16x32_bf16 v[114:117], v[192:195], v[208:211], v[114:117]
	v_mfma_f32_16x16x32_bf16 v[110:113], v[184:187], v[216:219], v[110:113]
	v_mfma_f32_16x16x32_bf16 v[106:109], v[192:195], v[216:219], v[106:109]
	v_mfma_f32_16x16x32_bf16 v[102:105], v[184:187], v[224:227], v[102:105]
	v_mfma_f32_16x16x32_bf16 v[98:101], v[192:195], v[224:227], v[98:101]
	s_setprio 0
	s_barrier
	s_add_i32 m0, s45, 0x10000
	s_add_u32 s30, s6, s50
	s_addc_u32 s31, s7, 0
	ds_read_b128 v[228:231], v156
	ds_read_b128 v[232:235], v156 offset:1024
	ds_read_b128 v[236:239], v156 offset:2048
	ds_read_b128 v[240:243], v156 offset:3072
	global_load_lds_dwordx4 v245, s[30:31]
	s_add_i32 m0, s45, 0x12000
	s_add_i32 s42, s42, 2
	global_load_lds_dwordx4 v246, s[30:31]
	s_barrier
	s_waitcnt lgkmcnt(0)
	s_setprio 1
	v_mfma_f32_16x16x32_bf16 v[94:97], v[228:231], v[196:199], v[94:97]
	v_mfma_f32_16x16x32_bf16 v[90:93], v[236:239], v[196:199], v[90:93]
	v_mfma_f32_16x16x32_bf16 v[86:89], v[228:231], v[204:207], v[86:89]
	v_mfma_f32_16x16x32_bf16 v[82:85], v[236:239], v[204:207], v[82:85]
	v_mfma_f32_16x16x32_bf16 v[78:81], v[228:231], v[212:215], v[78:81]
	v_mfma_f32_16x16x32_bf16 v[74:77], v[236:239], v[212:215], v[74:77]
	v_mfma_f32_16x16x32_bf16 v[70:73], v[228:231], v[220:223], v[70:73]
	v_mfma_f32_16x16x32_bf16 v[66:69], v[236:239], v[220:223], v[66:69]
	v_mfma_f32_16x16x32_bf16 v[94:97], v[232:235], v[200:203], v[94:97]
	v_mfma_f32_16x16x32_bf16 v[90:93], v[240:243], v[200:203], v[90:93]
	v_mfma_f32_16x16x32_bf16 v[86:89], v[232:235], v[208:211], v[86:89]
	v_mfma_f32_16x16x32_bf16 v[82:85], v[240:243], v[208:211], v[82:85]
	v_mfma_f32_16x16x32_bf16 v[78:81], v[232:235], v[216:219], v[78:81]
	v_mfma_f32_16x16x32_bf16 v[74:77], v[240:243], v[216:219], v[74:77]
	v_mfma_f32_16x16x32_bf16 v[70:73], v[232:235], v[224:227], v[70:73]
	v_mfma_f32_16x16x32_bf16 v[66:69], v[240:243], v[224:227], v[66:69]
	s_setprio 0
	s_mov_b32 m0, s45
	s_add_u32 s30, s4, s50
	s_addc_u32 s31, s5, 0
	s_barrier
	ds_read_b128 v[196:199], v141 offset:16384
	ds_read_b128 v[200:203], v141 offset:17408
	ds_read_b128 v[204:207], v140 offset:16384
	ds_read_b128 v[208:211], v140 offset:17408
	ds_read_b128 v[212:215], v139 offset:16384
	ds_read_b128 v[216:219], v139 offset:17408
	ds_read_b128 v[220:223], v138 offset:16384
	ds_read_b128 v[224:227], v138 offset:17408
	global_load_lds_dwordx4 v168, s[30:31]
	s_add_i32 m0, s45, 0x2000
	s_nop 0
	global_load_lds_dwordx4 v169, s[30:31]
	s_barrier
	s_waitcnt lgkmcnt(0)
	s_setprio 1
	v_mfma_f32_16x16x32_bf16 v[62:65], v[180:183], v[196:199], v[62:65]
	v_mfma_f32_16x16x32_bf16 v[58:61], v[188:191], v[196:199], v[58:61]
	v_mfma_f32_16x16x32_bf16 v[54:57], v[180:183], v[204:207], v[54:57]
	v_mfma_f32_16x16x32_bf16 v[50:53], v[188:191], v[204:207], v[50:53]
	v_mfma_f32_16x16x32_bf16 v[46:49], v[180:183], v[212:215], v[46:49]
	v_mfma_f32_16x16x32_bf16 v[42:45], v[188:191], v[212:215], v[42:45]
	v_mfma_f32_16x16x32_bf16 v[38:41], v[180:183], v[220:223], v[38:41]
	v_mfma_f32_16x16x32_bf16 v[34:37], v[188:191], v[220:223], v[34:37]
	v_mfma_f32_16x16x32_bf16 v[62:65], v[184:187], v[200:203], v[62:65]
	v_mfma_f32_16x16x32_bf16 v[58:61], v[192:195], v[200:203], v[58:61]
	v_mfma_f32_16x16x32_bf16 v[54:57], v[184:187], v[208:211], v[54:57]
	v_mfma_f32_16x16x32_bf16 v[50:53], v[192:195], v[208:211], v[50:53]
	v_mfma_f32_16x16x32_bf16 v[46:49], v[184:187], v[216:219], v[46:49]
	v_mfma_f32_16x16x32_bf16 v[42:45], v[192:195], v[216:219], v[42:45]
	v_mfma_f32_16x16x32_bf16 v[38:41], v[184:187], v[224:227], v[38:41]
	v_mfma_f32_16x16x32_bf16 v[34:37], v[192:195], v[224:227], v[34:37]
	s_setprio 0
	s_barrier
	s_add_i32 m0, s45, 0x14000
	s_add_u32 s30, s8, s50
	s_addc_u32 s31, s9, 0
	global_load_lds_dwordx4 v245, s[30:31]
	s_add_i32 m0, s45, 0x16000
	s_nop 0
	global_load_lds_dwordx4 v246, s[30:31]
	s_waitcnt vmcnt(6)
	s_barrier
; #define WAIT_V(n) asm volatile("s_waitcnt vmcnt(%0)" ::"n"(n) : "memory")
; #define WAIT_L(n) asm volatile("s_waitcnt lgkmcnt(%0)" ::"n"(n) : "memory")
; #define STAGE(P, BASE, OFF, kt) do { \
;     __builtin_amdgcn_global_load_lds((const unsigned*)((BASE) + (OFF[0] + (unsigned)(kt) * BK)), (unsigned*)((char*)(P) + wid * 1024), 16, 0, 0); \
;     __builtin_amdgcn_global_load_lds((const unsigned*)((BASE) + (OFF[1] + (unsigned)(kt) * BK)), (unsigned*)((char*)(P) + wid * 1024 + 8192), 16, 0, 0); } while (0)
; #define LDA(dst, b, h) for (int m = 0; m < 4; ++m) for (int k = 0; k < 2; ++k) \
;     dst[m][k] = *reinterpret_cast<const bf16x8*>((char*)SA(b, h) + lds_byte(wr * 64 + m * 16 + fr, k * 32 + fq * 8))
; #define LDB(dst, b, h) for (int n = 0; n < 2; ++n) for (int k = 0; k < 2; ++k) \
;     dst[n][k] = *reinterpret_cast<const bf16x8*>((char*)SB(b, h) + lds_byte(wc * 32 + n * 16 + fr, k * 32 + fq * 8))
; #define MMA(ai, bj, At_, Bt_) do { __builtin_amdgcn_s_setprio(1); \
;     for (int m = 0; m < 4; ++m) for (int n = 0; n < 2; ++n) for (int k = 0; k < 2; ++k) \
;       acc[ai][bj][m][n] = __builtin_amdgcn_mfma_f32_16x16x32_bf16(Bt_[n][k], At_[m][k], acc[ai][bj][m][n], 0, 0, 0); \
;     __builtin_amdgcn_s_setprio(0); } while (0)
; #define BAR __builtin_amdgcn_s_barrier()
; #define SCHED __builtin_amdgcn_sched_barrier(0)
; DEVI void gemm_tile(const Params& p, int layer, const u16* __restrict__ A, unsigned lda, const u16* __restrict__ Bt, unsigned ldb, int K,
;                     int brow, int bcol, int ekind, const int tid_) {
;     ...
;     WAIT_V(6); BAR; MMA(1, 1, At, B1); BAR;
;     LDB(B0, 1, 0); SCHED; LDA(At, 1, 0); STAGE(SA(0, 1), A1, offA, t + 2);
;     WAIT_L(8); BAR; WAIT_L(0); MMA(0, 0, At, B0); BAR; SCHED;
;     LDB(B1, 1, 1); STAGE(SB(1, 0), B0p, offB, t + 3);
;     BAR; WAIT_L(0); MMA(0, 1, At, B1); BAR;
;     LDA(At, 1, 1); STAGE(SA(1, 0), A0, offA, t + 3);
	s_setprio 1
	v_mfma_f32_16x16x32_bf16 v[30:33], v[228:231], v[196:199], v[30:33]
	v_mfma_f32_16x16x32_bf16 v[26:29], v[236:239], v[196:199], v[26:29]
	v_mfma_f32_16x16x32_bf16 v[22:25], v[228:231], v[204:207], v[22:25]
	v_mfma_f32_16x16x32_bf16 v[18:21], v[236:239], v[204:207], v[18:21]
	v_mfma_f32_16x16x32_bf16 v[14:17], v[228:231], v[212:215], v[14:17]
	v_mfma_f32_16x16x32_bf16 v[10:13], v[236:239], v[212:215], v[10:13]
	v_mfma_f32_16x16x32_bf16 v[6:9], v[228:231], v[220:223], v[6:9]
	v_mfma_f32_16x16x32_bf16 v[2:5], v[236:239], v[220:223], v[2:5]
	v_mfma_f32_16x16x32_bf16 v[30:33], v[232:235], v[200:203], v[30:33]
	v_mfma_f32_16x16x32_bf16 v[26:29], v[240:243], v[200:203], v[26:29]
	v_mfma_f32_16x16x32_bf16 v[22:25], v[232:235], v[208:211], v[22:25]
	v_mfma_f32_16x16x32_bf16 v[18:21], v[240:243], v[208:211], v[18:21]
	v_mfma_f32_16x16x32_bf16 v[14:17], v[232:235], v[216:219], v[14:17]
	v_mfma_f32_16x16x32_bf16 v[10:13], v[240:243], v[216:219], v[10:13]
	v_mfma_f32_16x16x32_bf16 v[6:9], v[232:235], v[224:227], v[6:9]
	v_mfma_f32_16x16x32_bf16 v[2:5], v[240:243], v[224:227], v[2:5]
	s_setprio 0
	s_barrier
	ds_read_b128 v[180:183], v147
	ds_read_b128 v[184:187], v147 offset:1024
	ds_read_b128 v[188:191], v147 offset:2048
	ds_read_b128 v[192:195], v147 offset:3072
	s_add_i32 m0, s45, 0x4000
	s_add_u32 s30, s2, s50
	s_addc_u32 s31, s3, 0
	ds_read_b128 v[196:199], v141 offset:32768
	ds_read_b128 v[200:203], v141 offset:33792
	ds_read_b128 v[204:207], v140 offset:32768
	ds_read_b128 v[208:211], v140 offset:33792
	ds_read_b128 v[212:215], v139 offset:32768
	ds_read_b128 v[216:219], v139 offset:33792
	ds_read_b128 v[220:223], v138 offset:32768
	ds_read_b128 v[224:227], v138 offset:33792
	global_load_lds_dwordx4 v168, s[30:31]
	s_add_i32 m0, s45, 0x6000
	s_nop 0
	global_load_lds_dwordx4 v169, s[30:31]
	s_waitcnt lgkmcnt(8)
	s_barrier
	s_waitcnt lgkmcnt(0)
	s_setprio 1
	v_mfma_f32_16x16x32_bf16 v[126:129], v[180:183], v[196:199], v[126:129]
	v_mfma_f32_16x16x32_bf16 v[122:125], v[188:191], v[196:199], v[122:125]
	v_mfma_f32_16x16x32_bf16 v[118:121], v[180:183], v[204:207], v[118:121]
	v_mfma_f32_16x16x32_bf16 v[114:117], v[188:191], v[204:207], v[114:117]
	v_mfma_f32_16x16x32_bf16 v[110:113], v[180:183], v[212:215], v[110:113]
	v_mfma_f32_16x16x32_bf16 v[106:109], v[188:191], v[212:215], v[106:109]
	v_mfma_f32_16x16x32_bf16 v[102:105], v[180:183], v[220:223], v[102:105]
	v_mfma_f32_16x16x32_bf16 v[98:101], v[188:191], v[220:223], v[98:101]
	v_mfma_f32_16x16x32_bf16 v[126:129], v[184:187], v[200:203], v[126:129]
	v_mfma_f32_16x16x32_bf16 v[122:125], v[192:195], v[200:203], v[122:125]
	v_mfma_f32_16x16x32_bf16 v[118:121], v[184:187], v[208:211], v[118:121]
	v_mfma_f32_16x16x32_bf16 v[114:117], v[192:195], v[208:211], v[114:117]
	v_mfma_f32_16x16x32_bf16 v[110:113], v[184:187], v[216:219], v[110:113]
	v_mfma_f32_16x16x32_bf16 v[106:109], v[192:195], v[216:219], v[106:109]
	v_mfma_f32_16x16x32_bf16 v[102:105], v[184:187], v[224:227], v[102:105]
	v_mfma_f32_16x16x32_bf16 v[98:101], v[192:195], v[224:227], v[98:101]
	s_setprio 0
	s_barrier
	s_add_i32 m0, s45, 0x18000
	s_add_u32 s30, s6, s50
	s_addc_u32 s31, s7, 0
	ds_read_b128 v[228:231], v142
	ds_read_b128 v[232:235], v142 offset:1024
	ds_read_b128 v[236:239], v142 offset:2048
	ds_read_b128 v[240:243], v142 offset:3072
	global_load_lds_dwordx4 v247, s[30:31]
	s_add_i32 m0, s45, 0x1a000
	s_nop 0
	global_load_lds_dwordx4 v248, s[30:31]
	s_barrier
	s_waitcnt lgkmcnt(0)
	s_setprio 1
	v_mfma_f32_16x16x32_bf16 v[94:97], v[228:231], v[196:199], v[94:97]
	v_mfma_f32_16x16x32_bf16 v[90:93], v[236:239], v[196:199], v[90:93]
	v_mfma_f32_16x16x32_bf16 v[86:89], v[228:231], v[204:207], v[86:89]
	v_mfma_f32_16x16x32_bf16 v[82:85], v[236:239], v[204:207], v[82:85]
	v_mfma_f32_16x16x32_bf16 v[78:81], v[228:231], v[212:215], v[78:81]
	v_mfma_f32_16x16x32_bf16 v[74:77], v[236:239], v[212:215], v[74:77]
	v_mfma_f32_16x16x32_bf16 v[70:73], v[228:231], v[220:223], v[70:73]
	v_mfma_f32_16x16x32_bf16 v[66:69], v[236:239], v[220:223], v[66:69]
	v_mfma_f32_16x16x32_bf16 v[94:97], v[232:235], v[200:203], v[94:97]
	v_mfma_f32_16x16x32_bf16 v[90:93], v[240:243], v[200:203], v[90:93]
	v_mfma_f32_16x16x32_bf16 v[86:89], v[232:235], v[208:211], v[86:89]
	v_mfma_f32_16x16x32_bf16 v[82:85], v[240:243], v[208:211], v[82:85]
	v_mfma_f32_16x16x32_bf16 v[78:81], v[232:235], v[216:219], v[78:81]
	v_mfma_f32_16x16x32_bf16 v[74:77], v[240:243], v[216:219], v[74:77]
	v_mfma_f32_16x16x32_bf16 v[70:73], v[232:235], v[224:227], v[70:73]
	v_mfma_f32_16x16x32_bf16 v[66:69], v[240:243], v[224:227], v[66:69]
	s_setprio 0
	s_add_i32 m0, s45, 0x8000
	s_add_u32 s30, s4, s50
	s_addc_u32 s31, s5, 0
	s_barrier
	ds_read_b128 v[196:199], v141 offset:49152
	ds_read_b128 v[200:203], v141 offset:50176
	ds_read_b128 v[204:207], v140 offset:49152
	ds_read_b128 v[208:211], v140 offset:50176
	ds_read_b128 v[212:215], v139 offset:49152
	ds_read_b128 v[216:219], v139 offset:50176
	ds_read_b128 v[220:223], v138 offset:49152
	ds_read_b128 v[224:227], v138 offset:50176
	global_load_lds_dwordx4 v179, s[30:31]
	s_add_i32 m0, s45, 0xa000
	s_nop 0
	global_load_lds_dwordx4 v244, s[30:31]
	s_barrier
; #define WAIT_V(n) asm volatile("s_waitcnt vmcnt(%0)" ::"n"(n) : "memory")
; #define WAIT_L(n) asm volatile("s_waitcnt lgkmcnt(%0)" ::"n"(n) : "memory")
; #define STAGE(P, BASE, OFF, kt) do { \
;     __builtin_amdgcn_global_load_lds((const unsigned*)((BASE) + (OFF[0] + (unsigned)(kt) * BK)), (unsigned*)((char*)(P) + wid * 1024), 16, 0, 0); \
;     __builtin_amdgcn_global_load_lds((const unsigned*)((BASE) + (OFF[1] + (unsigned)(kt) * BK)), (unsigned*)((char*)(P) + wid * 1024 + 8192), 16, 0, 0); } while (0)
; #define LDA(dst, b, h) for (int m = 0; m < 4; ++m) for (int k = 0; k < 2; ++k) \
;     dst[m][k] = *reinterpret_cast<const bf16x8*>((char*)SA(b, h) + lds_byte(wr * 64 + m * 16 + fr, k * 32 + fq * 8))
; #define LDB(dst, b, h) for (int n = 0; n < 2; ++n) for (int k = 0; k < 2; ++k) \
;     dst[n][k] = *reinterpret_cast<const bf16x8*>((char*)SB(b, h) + lds_byte(wc * 32 + n * 16 + fr, k * 32 + fq * 8))
; #define MMA(ai, bj, At_, Bt_) do { __builtin_amdgcn_s_setprio(1); \
;     for (int m = 0; m < 4; ++m) for (int n = 0; n < 2; ++n) for (int k = 0; k < 2; ++k) \
;       acc[ai][bj][m][n] = __builtin_amdgcn_mfma_f32_16x16x32_bf16(Bt_[n][k], At_[m][k], acc[ai][bj][m][n], 0, 0, 0); \
;     __builtin_amdgcn_s_setprio(0); } while (0)
; #define BAR __builtin_amdgcn_s_barrier()
; #define SCHED __builtin_amdgcn_sched_barrier(0)
; DEVI void gemm_tile(const Params& p, int layer, const u16* __restrict__ A, unsigned lda, const u16* __restrict__ Bt, unsigned ldb, int K,
;                     int brow, int bcol, int ekind, const int tid_) {
;     ...
;     LDA(At, 1, 1); STAGE(SA(1, 0), A0, offA, t + 3);
;     BAR; WAIT_L(0); MMA(1, 0, At, B0); BAR; SCHED;
;     STAGE(SB(1, 1), B1p, offB, t + 3);
;     WAIT_V(6); BAR; MMA(1, 1, At, B1); BAR;
;   }
;   { LDB(B0, 0, 0); LDA(At, 0, 0); STAGE(SA(1, 1), A1, offA, nt - 1);
;     BAR; WAIT_L(0); MMA(0, 0, At, B0); BAR;
;     LDB(B1, 0, 1); BAR; WAIT_L(0); MMA(0, 1, At, B1); BAR;
	s_waitcnt lgkmcnt(0)
	s_setprio 1
	v_mfma_f32_16x16x32_bf16 v[62:65], v[180:183], v[196:199], v[62:65]
	v_mfma_f32_16x16x32_bf16 v[58:61], v[188:191], v[196:199], v[58:61]
	v_mfma_f32_16x16x32_bf16 v[54:57], v[180:183], v[204:207], v[54:57]
	v_mfma_f32_16x16x32_bf16 v[50:53], v[188:191], v[204:207], v[50:53]
	v_mfma_f32_16x16x32_bf16 v[46:49], v[180:183], v[212:215], v[46:49]
	v_mfma_f32_16x16x32_bf16 v[42:45], v[188:191], v[212:215], v[42:45]
	v_mfma_f32_16x16x32_bf16 v[38:41], v[180:183], v[220:223], v[38:41]
	v_mfma_f32_16x16x32_bf16 v[34:37], v[188:191], v[220:223], v[34:37]
	v_mfma_f32_16x16x32_bf16 v[62:65], v[184:187], v[200:203], v[62:65]
	v_mfma_f32_16x16x32_bf16 v[58:61], v[192:195], v[200:203], v[58:61]
	v_mfma_f32_16x16x32_bf16 v[54:57], v[184:187], v[208:211], v[54:57]
	v_mfma_f32_16x16x32_bf16 v[50:53], v[192:195], v[208:211], v[50:53]
	v_mfma_f32_16x16x32_bf16 v[46:49], v[184:187], v[216:219], v[46:49]
	v_mfma_f32_16x16x32_bf16 v[42:45], v[192:195], v[216:219], v[42:45]
	v_mfma_f32_16x16x32_bf16 v[38:41], v[184:187], v[224:227], v[38:41]
	v_mfma_f32_16x16x32_bf16 v[34:37], v[192:195], v[224:227], v[34:37]
	s_setprio 0
	s_barrier
	s_add_i32 m0, s45, 0x1c000
	s_add_u32 s30, s8, s50
	s_addc_u32 s31, s9, 0
	global_load_lds_dwordx4 v247, s[30:31]
	s_add_i32 m0, s45, 0x1e000
	s_nop 0
	global_load_lds_dwordx4 v248, s[30:31]
	s_waitcnt vmcnt(6)
	s_barrier
	s_setprio 1
	v_mfma_f32_16x16x32_bf16 v[30:33], v[228:231], v[196:199], v[30:33]
	v_mfma_f32_16x16x32_bf16 v[26:29], v[236:239], v[196:199], v[26:29]
	v_mfma_f32_16x16x32_bf16 v[22:25], v[228:231], v[204:207], v[22:25]
	v_mfma_f32_16x16x32_bf16 v[18:21], v[236:239], v[204:207], v[18:21]
	v_mfma_f32_16x16x32_bf16 v[14:17], v[228:231], v[212:215], v[14:17]
	v_mfma_f32_16x16x32_bf16 v[10:13], v[236:239], v[212:215], v[10:13]
	v_mfma_f32_16x16x32_bf16 v[6:9], v[228:231], v[220:223], v[6:9]
	v_mfma_f32_16x16x32_bf16 v[2:5], v[236:239], v[220:223], v[2:5]
	v_mfma_f32_16x16x32_bf16 v[30:33], v[232:235], v[200:203], v[30:33]
	v_mfma_f32_16x16x32_bf16 v[26:29], v[240:243], v[200:203], v[26:29]
	v_mfma_f32_16x16x32_bf16 v[22:25], v[232:235], v[208:211], v[22:25]
	v_mfma_f32_16x16x32_bf16 v[18:21], v[240:243], v[208:211], v[18:21]
	v_mfma_f32_16x16x32_bf16 v[14:17], v[232:235], v[216:219], v[14:17]
	v_mfma_f32_16x16x32_bf16 v[10:13], v[240:243], v[216:219], v[10:13]
	v_mfma_f32_16x16x32_bf16 v[6:9], v[232:235], v[224:227], v[6:9]
	v_mfma_f32_16x16x32_bf16 v[2:5], v[240:243], v[224:227], v[2:5]
	s_setprio 0
	s_addk_i32 s11, 0x80
	s_cmp_lt_u32 s42, s10
	s_barrier
	s_cbranch_scc1 .LBB0_313
	s_movk_i32 s30, 0x604f
	v_readlane_b32 s31, v254, 43
	v_readlane_b32 s50, v254, 44
	s_sub_i32 s4, s66, 64
	v_add_u32_e32 v0, s4, v130
	v_readfirstlane_b32 s5, v164
	v_lshl_add_u64 v[144:145], v[0:1], 1, s[2:3]
	s_mov_b32 m0, s5
	v_add_u32_e32 v0, s4, v132
	ds_read_b128 v[148:151], v161
	ds_read_b128 v[152:155], v161 offset:1024
	ds_read_b128 v[180:183], v161 offset:2048
	ds_read_b128 v[158:161], v161 offset:3072
	ds_read_b128 v[184:187], v141
	ds_read_b128 v[188:191], v141 offset:1024
	ds_read_b128 v[192:195], v140
	ds_read_b128 v[196:199], v140 offset:1024
	ds_read_b128 v[200:203], v139
	ds_read_b128 v[204:207], v139 offset:1024
	ds_read_b128 v[208:211], v138
	ds_read_b128 v[212:215], v138 offset:1024
	global_load_lds_dwordx4 v[144:145], off
	v_lshl_add_u64 v[144:145], v[0:1], 1, s[2:3]
	v_readfirstlane_b32 s2, v165
	s_mov_b32 m0, s2
	s_nop 0
	global_load_lds_dwordx4 v[144:145], off
	s_barrier
	s_waitcnt lgkmcnt(0)
	s_setprio 1
	v_mfma_f32_16x16x32_bf16 v[126:129], v[148:151], v[184:187], v[126:129]
	v_mfma_f32_16x16x32_bf16 v[122:125], v[180:183], v[184:187], v[122:125]
	v_mfma_f32_16x16x32_bf16 v[118:121], v[148:151], v[192:195], v[118:121]
	v_mfma_f32_16x16x32_bf16 v[114:117], v[180:183], v[192:195], v[114:117]
	v_mfma_f32_16x16x32_bf16 v[102:105], v[148:151], v[208:211], v[102:105]
	v_mfma_f32_16x16x32_bf16 v[98:101], v[180:183], v[208:211], v[98:101]
	v_mfma_f32_16x16x32_bf16 v[126:129], v[152:155], v[188:191], v[126:129]
	v_mfma_f32_16x16x32_bf16 v[122:125], v[158:161], v[188:191], v[122:125]
	v_mfma_f32_16x16x32_bf16 v[118:121], v[152:155], v[196:199], v[118:121]
	v_mfma_f32_16x16x32_bf16 v[114:117], v[158:161], v[196:199], v[114:117]
	v_mfma_f32_16x16x32_bf16 v[110:113], v[148:151], v[200:203], v[110:113]
	v_mfma_f32_16x16x32_bf16 v[106:109], v[180:183], v[200:203], v[106:109]
	v_mfma_f32_16x16x32_bf16 v[102:105], v[152:155], v[212:215], v[102:105]
	v_mfma_f32_16x16x32_bf16 v[98:101], v[158:161], v[212:215], v[98:101]
	v_mfma_f32_16x16x32_bf16 v[162:165], v[152:155], v[204:207], v[110:113]
	v_mfma_f32_16x16x32_bf16 v[216:219], v[158:161], v[204:207], v[106:109]
	s_setprio 0
	s_barrier
	s_nop 1
	ds_read_b128 v[106:109], v156
	ds_read_b128 v[110:113], v156 offset:1024
	ds_read_b128 v[220:223], v156 offset:2048
	ds_read_b128 v[224:227], v156 offset:3072
	s_barrier
	s_waitcnt lgkmcnt(0)
	s_setprio 1
	v_mfma_f32_16x16x32_bf16 v[86:89], v[106:109], v[192:195], v[86:89]
	v_mfma_f32_16x16x32_bf16 v[82:85], v[220:223], v[192:195], v[82:85]
	v_mfma_f32_16x16x32_bf16 v[70:73], v[106:109], v[208:211], v[70:73]
	v_mfma_f32_16x16x32_bf16 v[66:69], v[220:223], v[208:211], v[66:69]
	v_mfma_f32_16x16x32_bf16 v[94:97], v[106:109], v[184:187], v[94:97]
	v_mfma_f32_16x16x32_bf16 v[90:93], v[220:223], v[184:187], v[90:93]
	v_mfma_f32_16x16x32_bf16 v[86:89], v[110:113], v[196:199], v[86:89]
	v_mfma_f32_16x16x32_bf16 v[82:85], v[224:227], v[196:199], v[82:85]
	v_mfma_f32_16x16x32_bf16 v[78:81], v[106:109], v[200:203], v[78:81]
	v_mfma_f32_16x16x32_bf16 v[74:77], v[220:223], v[200:203], v[74:77]
	v_mfma_f32_16x16x32_bf16 v[70:73], v[110:113], v[212:215], v[70:73]
	v_mfma_f32_16x16x32_bf16 v[66:69], v[224:227], v[212:215], v[66:69]
	v_mfma_f32_16x16x32_bf16 v[228:231], v[110:113], v[188:191], v[94:97]
	v_mfma_f32_16x16x32_bf16 v[184:187], v[224:227], v[188:191], v[90:93]
	v_mfma_f32_16x16x32_bf16 v[188:191], v[110:113], v[204:207], v[78:81]
	v_mfma_f32_16x16x32_bf16 v[192:195], v[224:227], v[204:207], v[74:77]
	s_setprio 0
	s_barrier
; #define WAIT_V(n) asm volatile("s_waitcnt vmcnt(%0)" ::"n"(n) : "memory")
; #define WAIT_L(n) asm volatile("s_waitcnt lgkmcnt(%0)" ::"n"(n) : "memory")
; #define LDA(dst, b, h) for (int m = 0; m < 4; ++m) for (int k = 0; k < 2; ++k) \
;     dst[m][k] = *reinterpret_cast<const bf16x8*>((char*)SA(b, h) + lds_byte(wr * 64 + m * 16 + fr, k * 32 + fq * 8))
; #define LDB(dst, b, h) for (int n = 0; n < 2; ++n) for (int k = 0; k < 2; ++k) \
;     dst[n][k] = *reinterpret_cast<const bf16x8*>((char*)SB(b, h) + lds_byte(wc * 32 + n * 16 + fr, k * 32 + fq * 8))
; #define MMA(ai, bj, At_, Bt_) do { __builtin_amdgcn_s_setprio(1); \
;     for (int m = 0; m < 4; ++m) for (int n = 0; n < 2; ++n) for (int k = 0; k < 2; ++k) \
;       acc[ai][bj][m][n] = __builtin_amdgcn_mfma_f32_16x16x32_bf16(Bt_[n][k], At_[m][k], acc[ai][bj][m][n], 0, 0, 0); \
;     __builtin_amdgcn_s_setprio(0); } while (0)
; #define BAR __builtin_amdgcn_s_barrier()
; DEVI void gemm_tile(const Params& p, int layer, const u16* __restrict__ A, unsigned lda, const u16* __restrict__ Bt, unsigned ldb, int K,
;                     int brow, int bcol, int ekind, const int tid_) {
;     ...
;     LDA(At, 0, 1); WAIT_V(4); BAR; WAIT_L(0); MMA(1, 0, At, B0); MMA(1, 1, At, B1); BAR; }
;   { LDB(B0, 1, 0); LDA(At, 1, 0); WAIT_V(2); BAR; WAIT_L(0); MMA(0, 0, At, B0); BAR;
	s_nop 0
	ds_read_b128 v[74:77], v141 offset:16384
	ds_read_b128 v[78:81], v141 offset:17408
	ds_read_b128 v[90:93], v140 offset:16384
	ds_read_b128 v[94:97], v140 offset:17408
	ds_read_b128 v[196:199], v139 offset:16384
	ds_read_b128 v[200:203], v139 offset:17408
	ds_read_b128 v[204:207], v138 offset:16384
	ds_read_b128 v[208:211], v138 offset:17408
	s_waitcnt vmcnt(4)
	s_barrier
	s_waitcnt lgkmcnt(0)
	s_setprio 1
	v_mfma_f32_16x16x32_bf16 v[62:65], v[148:151], v[74:77], v[62:65]
	v_mfma_f32_16x16x32_bf16 v[58:61], v[180:183], v[74:77], v[58:61]
	v_mfma_f32_16x16x32_bf16 v[54:57], v[148:151], v[90:93], v[54:57]
	v_mfma_f32_16x16x32_bf16 v[50:53], v[180:183], v[90:93], v[50:53]
	v_mfma_f32_16x16x32_bf16 v[38:41], v[148:151], v[204:207], v[38:41]
	v_mfma_f32_16x16x32_bf16 v[34:37], v[180:183], v[204:207], v[34:37]
	v_mfma_f32_16x16x32_bf16 v[62:65], v[152:155], v[78:81], v[62:65]
	v_mfma_f32_16x16x32_bf16 v[58:61], v[158:161], v[78:81], v[58:61]
	v_mfma_f32_16x16x32_bf16 v[54:57], v[152:155], v[94:97], v[54:57]
	v_mfma_f32_16x16x32_bf16 v[50:53], v[158:161], v[94:97], v[50:53]
	v_mfma_f32_16x16x32_bf16 v[46:49], v[148:151], v[196:199], v[46:49]
	v_mfma_f32_16x16x32_bf16 v[42:45], v[180:183], v[196:199], v[42:45]
	v_mfma_f32_16x16x32_bf16 v[38:41], v[152:155], v[208:211], v[38:41]
	v_mfma_f32_16x16x32_bf16 v[34:37], v[158:161], v[208:211], v[34:37]
	v_mfma_f32_16x16x32_bf16 v[212:215], v[152:155], v[200:203], v[46:49]
	v_mfma_f32_16x16x32_bf16 v[232:235], v[158:161], v[200:203], v[42:45]
	s_setprio 0
	s_setprio 1
	v_mfma_f32_16x16x32_bf16 v[22:25], v[106:109], v[90:93], v[22:25]
	v_mfma_f32_16x16x32_bf16 v[18:21], v[220:223], v[90:93], v[18:21]
	v_mfma_f32_16x16x32_bf16 v[6:9], v[106:109], v[204:207], v[6:9]
	v_mfma_f32_16x16x32_bf16 v[2:5], v[220:223], v[204:207], v[2:5]
	v_mfma_f32_16x16x32_bf16 v[30:33], v[106:109], v[74:77], v[30:33]
	v_mfma_f32_16x16x32_bf16 v[26:29], v[220:223], v[74:77], v[26:29]
	v_mfma_f32_16x16x32_bf16 v[22:25], v[110:113], v[94:97], v[22:25]
	v_mfma_f32_16x16x32_bf16 v[18:21], v[224:227], v[94:97], v[18:21]
	v_mfma_f32_16x16x32_bf16 v[14:17], v[106:109], v[196:199], v[14:17]
	v_mfma_f32_16x16x32_bf16 v[10:13], v[220:223], v[196:199], v[10:13]
	v_mfma_f32_16x16x32_bf16 v[6:9], v[110:113], v[208:211], v[6:9]
	v_mfma_f32_16x16x32_bf16 v[2:5], v[224:227], v[208:211], v[2:5]
	v_mfma_f32_16x16x32_bf16 v[148:151], v[110:113], v[78:81], v[30:33]
	v_mfma_f32_16x16x32_bf16 v[152:155], v[224:227], v[78:81], v[26:29]
	v_mfma_f32_16x16x32_bf16 v[156:159], v[110:113], v[200:203], v[14:17]
	v_mfma_f32_16x16x32_bf16 v[180:183], v[224:227], v[200:203], v[10:13]
	s_setprio 0
	s_barrier
	s_nop 0
	ds_read_b128 v[10:13], v147
	ds_read_b128 v[14:17], v147 offset:1024
	ds_read_b128 v[196:199], v147 offset:2048
	ds_read_b128 v[200:203], v147 offset:3072
	ds_read_b128 v[26:29], v141 offset:32768
	ds_read_b128 v[30:33], v141 offset:33792
	ds_read_b128 v[42:45], v140 offset:32768
	ds_read_b128 v[46:49], v140 offset:33792
	ds_read_b128 v[204:207], v139 offset:32768
	ds_read_b128 v[208:211], v139 offset:33792
	ds_read_b128 v[220:223], v138 offset:32768
	ds_read_b128 v[224:227], v138 offset:33792
	s_waitcnt vmcnt(2)
	s_barrier
	s_waitcnt lgkmcnt(0)
	s_setprio 1
	v_mfma_f32_16x16x32_bf16 v[74:77], v[10:13], v[26:29], v[126:129]
	v_mfma_f32_16x16x32_bf16 v[126:129], v[14:17], v[30:33], v[74:77]
	v_mfma_f32_16x16x32_bf16 v[74:77], v[196:199], v[26:29], v[122:125]
	v_mfma_f32_16x16x32_bf16 v[122:125], v[200:203], v[30:33], v[74:77]
	v_mfma_f32_16x16x32_bf16 v[74:77], v[10:13], v[42:45], v[118:121]
	v_mfma_f32_16x16x32_bf16 v[110:113], v[14:17], v[46:49], v[74:77]
	v_mfma_f32_16x16x32_bf16 v[74:77], v[196:199], v[42:45], v[114:117]
	v_mfma_f32_16x16x32_bf16 v[106:109], v[200:203], v[46:49], v[74:77]
	v_mfma_f32_16x16x32_bf16 v[74:77], v[10:13], v[204:207], v[162:165]
	v_mfma_f32_16x16x32_bf16 v[94:97], v[14:17], v[208:211], v[74:77]
	v_mfma_f32_16x16x32_bf16 v[74:77], v[196:199], v[204:207], v[216:219]
	v_mfma_f32_16x16x32_bf16 v[90:93], v[200:203], v[208:211], v[74:77]
	v_mfma_f32_16x16x32_bf16 v[74:77], v[10:13], v[220:223], v[102:105]
	v_mfma_f32_16x16x32_bf16 v[78:81], v[14:17], v[224:227], v[74:77]
	v_mfma_f32_16x16x32_bf16 v[74:77], v[196:199], v[220:223], v[98:101]
	v_mfma_f32_16x16x32_bf16 v[74:77], v[200:203], v[224:227], v[74:77]
	s_setprio 0
	s_barrier
; #define WAIT_V(n) asm volatile("s_waitcnt vmcnt(%0)" ::"n"(n) : "memory")
; #define WAIT_L(n) asm volatile("s_waitcnt lgkmcnt(%0)" ::"n"(n) : "memory")
; #define LDA(dst, b, h) for (int m = 0; m < 4; ++m) for (int k = 0; k < 2; ++k) \
;     dst[m][k] = *reinterpret_cast<const bf16x8*>((char*)SA(b, h) + lds_byte(wr * 64 + m * 16 + fr, k * 32 + fq * 8))
; #define LDB(dst, b, h) for (int n = 0; n < 2; ++n) for (int k = 0; k < 2; ++k) \
;     dst[n][k] = *reinterpret_cast<const bf16x8*>((char*)SB(b, h) + lds_byte(wc * 32 + n * 16 + fr, k * 32 + fq * 8))
; #define MMA(ai, bj, At_, Bt_) do { __builtin_amdgcn_s_setprio(1); \
;     for (int m = 0; m < 4; ++m) for (int n = 0; n < 2; ++n) for (int k = 0; k < 2; ++k) \
;       acc[ai][bj][m][n] = __builtin_amdgcn_mfma_f32_16x16x32_bf16(Bt_[n][k], At_[m][k], acc[ai][bj][m][n], 0, 0, 0); \
;     __builtin_amdgcn_s_setprio(0); } while (0)
; #define BAR __builtin_amdgcn_s_barrier()
; DEVI void gemm_tile(const Params& p, int layer, const u16* __restrict__ A, unsigned lda, const u16* __restrict__ Bt, unsigned ldb, int K,
;                     int brow, int bcol, int ekind, const int tid_) {
;     ...
;   { LDB(B0, 1, 0); LDA(At, 1, 0); WAIT_V(2); BAR; WAIT_L(0); MMA(0, 0, At, B0); BAR;
;     LDB(B1, 1, 1); WAIT_V(0); BAR; WAIT_L(0); MMA(0, 1, At, B1); BAR;
;     LDA(At, 1, 1); BAR; WAIT_L(0); MMA(1, 0, At, B0); MMA(1, 1, At, B1); BAR; }
;   if (wr == 0) BAR;
	ds_read_b128 v[160:163], v142
	ds_read_b128 v[164:167], v142 offset:1024
	ds_read_b128 v[216:219], v142 offset:2048
	ds_read_b128 v[142:145], v142 offset:3072
	s_waitcnt vmcnt(0)
	s_barrier
	s_waitcnt lgkmcnt(0)
	s_setprio 1
	v_mfma_f32_16x16x32_bf16 v[98:101], v[160:163], v[26:29], v[228:231]
	v_mfma_f32_16x16x32_bf16 v[26:29], v[216:219], v[26:29], v[184:187]
	v_mfma_f32_16x16x32_bf16 v[114:117], v[142:145], v[30:33], v[26:29]
	v_mfma_f32_16x16x32_bf16 v[26:29], v[160:163], v[42:45], v[86:89]
	v_mfma_f32_16x16x32_bf16 v[102:105], v[164:167], v[46:49], v[26:29]
	v_mfma_f32_16x16x32_bf16 v[26:29], v[216:219], v[42:45], v[82:85]
	v_mfma_f32_16x16x32_bf16 v[118:121], v[164:167], v[30:33], v[98:101]
	v_mfma_f32_16x16x32_bf16 v[98:101], v[142:145], v[46:49], v[26:29]
	v_mfma_f32_16x16x32_bf16 v[26:29], v[160:163], v[204:207], v[188:191]
	v_mfma_f32_16x16x32_bf16 v[86:89], v[164:167], v[208:211], v[26:29]
	v_mfma_f32_16x16x32_bf16 v[26:29], v[216:219], v[204:207], v[192:195]
	v_mfma_f32_16x16x32_bf16 v[82:85], v[142:145], v[208:211], v[26:29]
	v_mfma_f32_16x16x32_bf16 v[26:29], v[160:163], v[220:223], v[70:73]
	v_mfma_f32_16x16x32_bf16 v[70:73], v[164:167], v[224:227], v[26:29]
	v_mfma_f32_16x16x32_bf16 v[26:29], v[216:219], v[220:223], v[66:69]
	v_mfma_f32_16x16x32_bf16 v[66:69], v[142:145], v[224:227], v[26:29]
	s_setprio 0
	s_barrier
	ds_read_b128 v[184:187], v141 offset:49152
	ds_read_b128 v[188:191], v141 offset:50176
	ds_read_b128 v[192:195], v140 offset:49152
	ds_read_b128 v[204:207], v140 offset:50176
	ds_read_b128 v[208:211], v139 offset:49152
	ds_read_b128 v[220:223], v139 offset:50176
	ds_read_b128 v[224:227], v138 offset:49152
	ds_read_b128 v[138:141], v138 offset:50176
	s_barrier
	s_waitcnt lgkmcnt(0)
	s_setprio 1
	v_mfma_f32_16x16x32_bf16 v[26:29], v[10:13], v[184:187], v[62:65]
	v_mfma_f32_16x16x32_bf16 v[62:65], v[14:17], v[188:191], v[26:29]
	v_mfma_f32_16x16x32_bf16 v[26:29], v[196:199], v[184:187], v[58:61]
	v_mfma_f32_16x16x32_bf16 v[58:61], v[200:203], v[188:191], v[26:29]
	v_mfma_f32_16x16x32_bf16 v[26:29], v[10:13], v[192:195], v[54:57]
	v_mfma_f32_16x16x32_bf16 v[46:49], v[14:17], v[204:207], v[26:29]
	v_mfma_f32_16x16x32_bf16 v[26:29], v[196:199], v[192:195], v[50:53]
	v_mfma_f32_16x16x32_bf16 v[42:45], v[200:203], v[204:207], v[26:29]
	v_mfma_f32_16x16x32_bf16 v[26:29], v[10:13], v[208:211], v[212:215]
	v_mfma_f32_16x16x32_bf16 v[10:13], v[10:13], v[224:227], v[38:41]
	v_mfma_f32_16x16x32_bf16 v[30:33], v[14:17], v[220:223], v[26:29]
	v_mfma_f32_16x16x32_bf16 v[26:29], v[196:199], v[208:211], v[232:235]
	v_mfma_f32_16x16x32_bf16 v[14:17], v[14:17], v[138:141], v[10:13]
	v_mfma_f32_16x16x32_bf16 v[10:13], v[196:199], v[224:227], v[34:37]
	v_mfma_f32_16x16x32_bf16 v[26:29], v[200:203], v[220:223], v[26:29]
	v_mfma_f32_16x16x32_bf16 v[10:13], v[200:203], v[138:141], v[10:13]
	s_setprio 0
	s_setprio 1
	v_mfma_f32_16x16x32_bf16 v[34:37], v[160:163], v[184:187], v[148:151]
	v_mfma_f32_16x16x32_bf16 v[54:57], v[164:167], v[188:191], v[34:37]
	v_mfma_f32_16x16x32_bf16 v[34:37], v[216:219], v[184:187], v[152:155]
	v_mfma_f32_16x16x32_bf16 v[18:21], v[216:219], v[192:195], v[18:21]
	v_mfma_f32_16x16x32_bf16 v[50:53], v[142:145], v[188:191], v[34:37]
	v_mfma_f32_16x16x32_bf16 v[22:25], v[160:163], v[192:195], v[22:25]
	v_mfma_f32_16x16x32_bf16 v[34:37], v[142:145], v[204:207], v[18:21]
	v_mfma_f32_16x16x32_bf16 v[18:21], v[160:163], v[208:211], v[156:159]
	v_mfma_f32_16x16x32_bf16 v[38:41], v[164:167], v[204:207], v[22:25]
	v_mfma_f32_16x16x32_bf16 v[22:25], v[164:167], v[220:223], v[18:21]
	v_mfma_f32_16x16x32_bf16 v[18:21], v[216:219], v[208:211], v[180:183]
	v_mfma_f32_16x16x32_bf16 v[6:9], v[160:163], v[224:227], v[6:9]
	v_mfma_f32_16x16x32_bf16 v[2:5], v[216:219], v[224:227], v[2:5]
	v_mfma_f32_16x16x32_bf16 v[18:21], v[142:145], v[220:223], v[18:21]
	v_mfma_f32_16x16x32_bf16 v[6:9], v[164:167], v[138:141], v[6:9]
	v_mfma_f32_16x16x32_bf16 v[2:5], v[142:145], v[138:141], v[2:5]
	s_setprio 0
	s_movk_i32 s2, 0x100
	v_cmp_gt_u32_e32 vcc, s2, v136
	s_barrier
	s_and_saveexec_b64 s[2:3], vcc
	s_cbranch_execz .LBB0_316
	s_barrier
